# GATE0: row sums of squares staged once per workgroup in LDS tables (full tile and part tile); epilogues read them by ds_read instead of 8 serialized global loads with vmcnt(0)
# baseline (speedup 1.0000x reference)
.LBB0_811:
	s_cmp_lt_i32 s30, 6
	s_waitcnt lgkmcnt(0)
	s_cselect_b64 s[62:63], -1, 0
	s_add_u32 s96, s28, 0x490000
	s_addc_u32 s2, s29, 0
	v_writelane_b32 v254, s2, 23
	s_add_u32 s2, s28, 0x4f0000
	s_addc_u32 s3, s29, 0
	v_writelane_b32 v254, s2, 19
	s_nop 1
	v_writelane_b32 v254, s3, 20
	s_add_u32 s2, s28, 0x51c000
	s_addc_u32 s3, s29, 0
	s_and_b64 s[0:1], s[62:63], s[0:1]
	v_writelane_b32 v254, s2, 24
	s_andn2_b64 vcc, exec, s[0:1]
	s_nop 0
	v_writelane_b32 v254, s3, 25
	s_cbranch_vccnz .LBB0_892
	v_mbcnt_lo_u32_b32 v232, -1, 0
	v_mbcnt_hi_u32_b32 v232, -1, v232
	v_readlane_b32 s98, v254, 13
	s_nop 3
	s_and_b32 s99, s16, 7
	s_lshl_b32 s99, s99, 3
	s_bfe_u32 s100, s16, 0x30003
	s_add_i32 s99, s99, s100
	s_lshl_b32 s99, s99, 8
	s_lshl_b32 s100, s98, 5
	s_add_i32 s99, s99, s100
	v_and_b32_e32 v233, 15, v232
	v_lshrrev_b32_e32 v234, 4, v232
	v_add_u32_e32 v235, s99, v233
	v_lshlrev_b32_e32 v235, 6, v235
	v_lshl_add_u32 v235, v234, 4, v235
	s_add_u32 s100, s28, 0x100000
	s_addc_u32 s101, s29, 0
	global_load_dwordx4 v[240:243], v235, s[100:101]
	global_load_dwordx4 v[244:247], v235, s[100:101] offset:1024
	s_and_b32 s99, s16, 7
	s_lshl_b32 s99, s99, 11
	s_bfe_u32 s100, s16, 0x40003
	s_lshl_b32 s100, s100, 7
	s_add_i32 s99, s99, s100
	s_lshl_b32 s100, s98, 4
	s_add_i32 s99, s99, s100
	v_add_u32_e32 v236, s99, v233
	v_lshlrev_b32_e32 v236, 6, v236
	v_lshl_add_u32 v236, v234, 4, v236
	s_add_u32 s100, s28, 0x100000
	s_addc_u32 s101, s29, 0
	global_load_dwordx4 v[248:251], v236, s[100:101]
	v_xor_b32_e32 v238, 16, v232
	v_lshlrev_b32_e32 v238, 2, v238
	v_xor_b32_e32 v239, 32, v232
	v_lshlrev_b32_e32 v239, 2, v239
	s_add_i32 s0, s17, -1
	s_cmp_lg_u32 s16, s0
	v_readlane_b32 s56, v254, 13
	v_mbcnt_lo_u32_b32 v5, -1, 0
	v_mbcnt_hi_u32_b32 v5, -1, v5
	s_cbranch_scc1 .LBB0_818
	s_lshl_b32 s0, s56, 1
	s_mov_b32 s1, 0
	s_lshl_b64 s[2:3], s[0:1], 12
	v_readlane_b32 s4, v254, 9
	v_readlane_b32 s5, v254, 10
	s_add_u32 s4, s4, s2
	v_lshlrev_b32_e32 v0, 2, v5
	s_addc_u32 s5, s5, s3
	v_readlane_b32 s6, v254, 21
	v_readlane_b32 s7, v254, 22
	s_add_u32 s6, s6, s2
	v_ashrrev_i32_e32 v1, 31, v0
	s_addc_u32 s7, s7, s3
	v_lshlrev_b64 v[0:1], 2, v[0:1]
	v_lshl_add_u64 v[34:35], s[6:7], 0, v[0:1]
	v_lshl_add_u64 v[2:3], s[4:5], 0, v[0:1]
	global_load_dwordx4 v[6:9], v[34:35], off
	global_load_dwordx4 v[10:13], v[2:3], off
	global_load_dwordx4 v[14:17], v[2:3], off offset:1024
	global_load_dwordx4 v[18:21], v[34:35], off offset:1024
	global_load_dwordx4 v[22:25], v[34:35], off offset:2048
	global_load_dwordx4 v[26:29], v[2:3], off offset:2048
	global_load_dwordx4 v[30:33], v[2:3], off offset:3072
	s_nop 0
	global_load_dwordx4 v[34:37], v[34:35], off offset:3072
	v_mbcnt_lo_u32_b32 v2, -1, 0
	v_mbcnt_hi_u32_b32 v2, -1, v2
	v_and_b32_e32 v4, 64, v2
	v_xor_b32_e32 v3, 16, v2
	v_add_u32_e32 v4, 64, v4
	s_waitcnt vmcnt(8)
	v_xor_b32_e32 v38, 32, v2
	v_cmp_lt_i32_e32 vcc, v3, v4
	s_add_u32 s2, s96, s2
	v_readlane_b32 s4, v254, 23
	v_cndmask_b32_e32 v3, v2, v3, vcc
	v_cmp_lt_i32_e32 vcc, v38, v4
	v_lshlrev_b32_e32 v3, 2, v3
	s_addc_u32 s3, s4, s3
	v_cndmask_b32_e32 v2, v2, v38, vcc
	v_lshlrev_b32_e32 v2, 2, v2
	v_cmp_eq_u32_e32 vcc, 0, v5
	s_waitcnt vmcnt(6)
	v_pk_add_f32 v[12:13], v[12:13], v[8:9]
	v_pk_add_f32 v[10:11], v[10:11], v[6:7]
	s_waitcnt vmcnt(4)
	v_pk_add_f32 v[16:17], v[16:17], v[20:21]
	v_pk_add_f32 v[14:15], v[14:15], v[18:19]
	s_waitcnt vmcnt(2)
	v_pk_add_f32 v[20:21], v[28:29], v[24:25]
	v_pk_add_f32 v[18:19], v[26:27], v[22:23]
	v_mul_f32_e32 v4, v11, v11
	v_mul_f32_e32 v6, v13, v13
	v_mul_f32_e32 v7, v15, v15
	v_mul_f32_e32 v8, v17, v17
	s_waitcnt vmcnt(0)
	v_pk_add_f32 v[24:25], v[32:33], v[36:37]
	v_pk_add_f32 v[22:23], v[30:31], v[34:35]
	v_mul_f32_e32 v9, v19, v19
	v_mul_f32_e32 v26, v21, v21
	v_fmac_f32_e32 v4, v10, v10
	v_fmac_f32_e32 v6, v12, v12
	v_fmac_f32_e32 v7, v14, v14
	v_fmac_f32_e32 v8, v16, v16
	v_mul_f32_e32 v27, v23, v23
	v_mul_f32_e32 v28, v25, v25
	v_fmac_f32_e32 v9, v18, v18
	v_fmac_f32_e32 v26, v20, v20
	v_add_f32_e32 v4, v4, v6
	v_add_f32_e32 v6, v7, v8
	v_fmac_f32_e32 v27, v22, v22
	v_fmac_f32_e32 v28, v24, v24
	v_add_f32_e32 v7, v9, v26
	v_add_f32_e32 v4, v4, v6
	v_add_f32_e32 v4, v4, v7
	v_add_f32_e32 v6, v27, v28
	v_add_f32_e32 v4, v4, v6
	v_lshl_add_u64 v[8:9], s[2:3], 0, v[0:1]
	global_store_dwordx4 v[8:9], v[10:13], off
	global_store_dwordx4 v[8:9], v[14:17], off offset:1024
	global_store_dwordx4 v[8:9], v[18:21], off offset:2048
	global_store_dwordx4 v[8:9], v[22:25], off offset:3072
	v_add_f32_dpp v4, v4, v4 quad_perm:[1,0,3,2] row_mask:0xf bank_mask:0xf bound_ctrl:1
	s_nop 1
	v_add_f32_dpp v4, v4, v4 quad_perm:[2,3,0,1] row_mask:0xf bank_mask:0xf bound_ctrl:1
	s_nop 1
	v_add_f32_dpp v4, v4, v4 row_half_mirror row_mask:0xf bank_mask:0xf bound_ctrl:1
	s_nop 1
	v_add_f32_dpp v4, v4, v4 row_mirror row_mask:0xf bank_mask:0xf bound_ctrl:1
	ds_bpermute_b32 v6, v3, v4
	s_waitcnt lgkmcnt(0)
	v_add_f32_e32 v4, v4, v6
	ds_bpermute_b32 v6, v2, v4
	s_and_saveexec_b64 s[2:3], vcc
	s_cbranch_execz .LBB0_815
	s_lshl_b32 s4, s0, 2
	s_waitcnt lgkmcnt(0)
	v_add_f32_e32 v4, v4, v6
	v_mov_b32_e32 v6, s4
	v_readlane_b32 s4, v254, 11
	v_readlane_b32 s5, v254, 12
	s_nop 4
	global_store_dword v6, v4, s[4:5]

.LBB0_852:
	v_cndmask_b32_e64 v0, 0, 1, s[2:3]
	v_cmp_ne_u32_e64 s[0:1], 1, v0
	s_andn2_b64 vcc, exec, s[2:3]
	v_readfirstlane_b32 s5, v30
	s_waitcnt vmcnt(0)
	v_add_f32_e32 v240, v241, v240
	v_add_f32_e32 v241, v242, v243
	v_add_f32_e32 v244, v245, v244
	v_add_f32_e32 v245, v246, v247
	v_add_f32_e32 v242, v244, v245
	v_add_f32_e32 v243, v240, v241
	ds_bpermute_b32 v247, v238, v243
	ds_bpermute_b32 v246, v238, v242
	s_waitcnt lgkmcnt(0)
	v_pk_add_f32 v[252:253], v[242:243], v[246:247]
	ds_bpermute_b32 v247, v239, v253
	ds_bpermute_b32 v246, v239, v252
	s_waitcnt lgkmcnt(0)
	v_pk_add_f32 v[252:253], v[252:253], v[246:247]
	s_lshl_b32 s99, s98, 7
	v_lshl_add_u32 v235, v233, 2, s99
	v_add_u32_e32 v235, 0x22800, v235
	ds_write_b32 v235, v253
	ds_write_b32 v235, v252 offset:64
	v_add_f32_e32 v248, v249, v248
	v_add_f32_e32 v249, v250, v251
	v_add_f32_e32 v248, v248, v249
	s_nop 0
	ds_bpermute_b32 v249, v238, v248
	s_waitcnt lgkmcnt(0)
	v_add_f32_e32 v248, v248, v249
	s_nop 0
	ds_bpermute_b32 v249, v239, v248
	s_waitcnt lgkmcnt(0)
	v_add_f32_e32 v248, v248, v249
	s_lshl_b32 s99, s98, 6
	v_lshl_add_u32 v236, v233, 2, s99
	v_add_u32_e32 v236, 0x22c00, v236
	ds_write_b32 v236, v248
	s_waitcnt lgkmcnt(0)
	s_waitcnt lgkmcnt(0)
	s_barrier
	s_cbranch_vccnz .LBB0_856
	s_mov_b64 s[2:3], 0
	s_cmpk_lt_i32 s16, 0x2c0
	s_mov_b64 s[6:7], 0
	s_cbranch_scc1 .LBB0_857
	s_and_b64 vcc, exec, s[2:3]
	s_cbranch_vccnz .LBB0_858

.LBB0_884:
	s_andn2_b64 vcc, exec, s[82:83]
	s_cbranch_vccnz .LBB0_890
	v_and_b32_e32 v129, 64, v186
	v_xor_b32_e32 v128, 16, v186
	v_add_u32_e32 v129, 64, v129
	v_cmp_lt_i32_e32 vcc, v128, v129
	v_add_u32_e32 v160, s2, v167
	v_ashrrev_i32_e32 v161, 31, v160
	v_cndmask_b32_e32 v128, v186, v128, vcc
	v_lshlrev_b32_e32 v166, 2, v128
	v_xor_b32_e32 v128, 32, v186
	v_cmp_lt_i32_e32 vcc, v128, v129
	v_add_u32_e32 v156, 32, v160
	v_ashrrev_i32_e32 v157, 31, v156
	v_cndmask_b32_e32 v128, v186, v128, vcc
	v_lshlrev_b32_e32 v170, 2, v128
	v_lshlrev_b32_e32 v231, 2, v167
	v_add_u32_e32 v231, 0x22c00, v231
	v_mov_b64_e32 v[158:159], s[18:19]
	v_add_u32_e32 v130, 16, v160
	v_ashrrev_i32_e32 v131, 31, v130
	s_nop 0
	ds_read_b32 v129, v231
	ds_read_b32 v128, v231 offset:64
	s_waitcnt lgkmcnt(0)
	v_pk_fma_f32 v[128:129], v[128:129], s[14:15], v[158:159] op_sel_hi:[1,0,0]
	v_add_u32_e32 v154, 48, v160
	v_ashrrev_i32_e32 v155, 31, v154
	v_mul_f32_e32 v131, 0x4b800000, v129
	v_cmp_gt_f32_e64 s[2:3], s81, v129
	v_cmp_gt_f32_e32 vcc, s81, v128
	s_nop 1
	v_cndmask_b32_e64 v129, v129, v131, s[2:3]
	v_rsq_f32_e32 v129, v129
	v_add_u32_e32 v164, s80, v175
	v_ashrrev_i32_e32 v165, 31, v164
	v_mul_f32_e32 v131, 0x45800000, v129
	v_cndmask_b32_e64 v150, v129, v131, s[2:3]
	v_mul_f32_e32 v129, 0x4b800000, v128
	v_cndmask_b32_e32 v128, v128, v129, vcc
	v_rsq_f32_e32 v128, v128
	v_pk_mul_f32 v[172:173], v[92:93], v[150:151] op_sel_hi:[1,0]
	v_pk_mul_f32 v[180:181], v[90:91], v[150:151] op_sel_hi:[1,0]
	v_mul_f32_e32 v129, 0x45800000, v128
	ds_read_b32 v153, v231 offset:128
	ds_read_b32 v152, v231 offset:192
	s_waitcnt lgkmcnt(0)
	v_pk_fma_f32 v[152:153], v[152:153], s[14:15], v[158:159] op_sel_hi:[1,0,0]
	v_cndmask_b32_e32 v128, v128, v129, vcc
	v_mul_f32_e32 v129, 0x4b800000, v153
	v_cmp_gt_f32_e64 s[2:3], s81, v153
	v_cmp_gt_f32_e32 vcc, s81, v152
	v_mov_b64_e32 v[162:163], s[8:9]
	v_cndmask_b32_e64 v129, v153, v129, s[2:3]
	v_rsq_f32_e32 v129, v129
	v_pk_mul_f32 v[178:179], v[88:89], v[150:151] op_sel_hi:[1,0]
	v_cvt_pk_bf16_f32 v176, v172, v173
	v_cvt_pk_bf16_f32 v178, v178, v179
	v_mul_f32_e32 v131, 0x45800000, v129
	v_cndmask_b32_e64 v158, v129, v131, s[2:3]
	v_mul_f32_e32 v129, 0x4b800000, v152
	v_cndmask_b32_e32 v129, v152, v129, vcc
	v_rsq_f32_e32 v129, v129
	v_mad_i64_i32 v[168:169], s[2:3], v160, s94, v[162:163]
	v_lshlrev_b64 v[160:161], 1, v[164:165]
	v_lshl_add_u64 v[164:165], v[168:169], 0, v[160:161]
	v_pk_mul_f32 v[168:169], v[94:95], v[150:151] op_sel_hi:[1,0]
	v_cvt_pk_bf16_f32 v179, v180, v181
	v_cvt_pk_bf16_f32 v177, v168, v169
	global_store_dwordx4 v[164:165], v[176:179], off
	v_pk_mul_f32 v[168:169], v[78:79], v[150:151] op_sel_hi:[1,0]
	v_pk_mul_f32 v[172:173], v[76:77], v[150:151] op_sel_hi:[1,0]
	v_pk_mul_f32 v[180:181], v[74:75], v[150:151] op_sel_hi:[1,0]
	v_pk_mul_f32 v[178:179], v[72:73], v[150:151] op_sel_hi:[1,0]
	v_mul_f32_e32 v131, 0x45800000, v129
	v_cvt_pk_bf16_f32 v176, v172, v173
	v_cvt_pk_bf16_f32 v177, v168, v169
	v_cvt_pk_bf16_f32 v178, v178, v179
	v_cvt_pk_bf16_f32 v179, v180, v181
	v_pk_mul_f32 v[168:169], v[30:31], v[150:151] op_sel_hi:[1,0]
	v_pk_mul_f32 v[172:173], v[28:29], v[150:151] op_sel_hi:[1,0]
	v_pk_mul_f32 v[180:181], v[26:27], v[150:151] op_sel_hi:[1,0]
	v_pk_mul_f32 v[150:151], v[24:25], v[150:151] op_sel_hi:[1,0]
	v_cndmask_b32_e32 v152, v129, v131, vcc
	global_store_dwordx4 v[164:165], v[176:179], off offset:256
	v_mad_i64_i32 v[130:131], s[2:3], v130, s94, v[162:163]
	s_nop 0
	v_cvt_pk_bf16_f32 v176, v172, v173
	v_cvt_pk_bf16_f32 v177, v168, v169
	v_cvt_pk_bf16_f32 v178, v150, v151
	v_cvt_pk_bf16_f32 v179, v180, v181
	global_store_dwordx4 v[164:165], v[176:179], off offset:512
	v_lshl_add_u64 v[150:151], v[130:131], 0, v[160:161]
	v_pk_mul_f32 v[130:131], v[86:87], v[128:129] op_sel_hi:[1,0]
	v_pk_mul_f32 v[164:165], v[84:85], v[128:129] op_sel_hi:[1,0]
	v_pk_mul_f32 v[168:169], v[82:83], v[128:129] op_sel_hi:[1,0]
	v_pk_mul_f32 v[172:173], v[80:81], v[128:129] op_sel_hi:[1,0]
	v_cvt_pk_bf16_f32 v176, v164, v165
	v_cvt_pk_bf16_f32 v177, v130, v131
	v_cvt_pk_bf16_f32 v178, v172, v173
	v_cvt_pk_bf16_f32 v179, v168, v169
	v_pk_mul_f32 v[130:131], v[62:63], v[128:129] op_sel_hi:[1,0]
	v_pk_mul_f32 v[164:165], v[60:61], v[128:129] op_sel_hi:[1,0]
	v_pk_mul_f32 v[168:169], v[58:59], v[128:129] op_sel_hi:[1,0]
	v_pk_mul_f32 v[172:173], v[56:57], v[128:129] op_sel_hi:[1,0]
	global_store_dwordx4 v[150:151], v[176:179], off
	s_nop 1
	v_cvt_pk_bf16_f32 v176, v164, v165
	v_cvt_pk_bf16_f32 v177, v130, v131
	v_cvt_pk_bf16_f32 v178, v172, v173
	v_cvt_pk_bf16_f32 v179, v168, v169
	v_pk_mul_f32 v[130:131], v[22:23], v[128:129] op_sel_hi:[1,0]
	v_pk_mul_f32 v[164:165], v[20:21], v[128:129] op_sel_hi:[1,0]
	v_pk_mul_f32 v[168:169], v[18:19], v[128:129] op_sel_hi:[1,0]
	v_pk_mul_f32 v[172:173], v[16:17], v[128:129] op_sel_hi:[1,0]
	v_cvt_pk_bf16_f32 v128, v164, v165
	v_cvt_pk_bf16_f32 v129, v130, v131
	v_cvt_pk_bf16_f32 v130, v172, v173
	v_cvt_pk_bf16_f32 v131, v168, v169
	global_store_dwordx4 v[150:151], v[128:131], off offset:512
	global_store_dwordx4 v[150:151], v[176:179], off offset:256
	v_pk_mul_f32 v[164:165], v[64:65], v[158:159] op_sel_hi:[1,0]
	v_mad_i64_i32 v[128:129], s[2:3], v156, s94, v[162:163]
	v_lshl_add_u64 v[150:151], v[128:129], 0, v[160:161]
	v_pk_mul_f32 v[130:131], v[70:71], v[158:159] op_sel_hi:[1,0]
	v_pk_mul_f32 v[128:129], v[68:69], v[158:159] op_sel_hi:[1,0]
	v_pk_mul_f32 v[156:157], v[66:67], v[158:159] op_sel_hi:[1,0]
	v_cvt_pk_bf16_f32 v128, v128, v129
	v_cvt_pk_bf16_f32 v129, v130, v131
	v_cvt_pk_bf16_f32 v130, v164, v165
	v_cvt_pk_bf16_f32 v131, v156, v157
	global_store_dwordx4 v[150:151], v[128:131], off
	v_pk_mul_f32 v[156:157], v[42:43], v[158:159] op_sel_hi:[1,0]
	v_pk_mul_f32 v[164:165], v[40:41], v[158:159] op_sel_hi:[1,0]
	v_pk_mul_f32 v[130:131], v[46:47], v[158:159] op_sel_hi:[1,0]
	v_pk_mul_f32 v[128:129], v[44:45], v[158:159] op_sel_hi:[1,0]
	s_nop 0
	v_cvt_pk_bf16_f32 v128, v128, v129
	v_cvt_pk_bf16_f32 v129, v130, v131
	v_cvt_pk_bf16_f32 v130, v164, v165
	v_cvt_pk_bf16_f32 v131, v156, v157
	global_store_dwordx4 v[150:151], v[128:131], off offset:256
	v_pk_mul_f32 v[156:157], v[10:11], v[158:159] op_sel_hi:[1,0]
	s_nop 0
	v_pk_mul_f32 v[130:131], v[14:15], v[158:159] op_sel_hi:[1,0]
	v_pk_mul_f32 v[128:129], v[12:13], v[158:159] op_sel_hi:[1,0]
	v_pk_mul_f32 v[158:159], v[8:9], v[158:159] op_sel_hi:[1,0]
	v_cvt_pk_bf16_f32 v128, v128, v129
	v_cvt_pk_bf16_f32 v129, v130, v131
	v_cvt_pk_bf16_f32 v130, v158, v159
	v_cvt_pk_bf16_f32 v131, v156, v157
	global_store_dwordx4 v[150:151], v[128:131], off offset:512
	v_pk_mul_f32 v[156:157], v[48:49], v[152:153] op_sel_hi:[1,0]
	s_nop 0
	v_mad_i64_i32 v[128:129], s[2:3], v154, s94, v[162:163]
	v_lshl_add_u64 v[150:151], v[128:129], 0, v[160:161]
	v_pk_mul_f32 v[130:131], v[54:55], v[152:153] op_sel_hi:[1,0]
	v_pk_mul_f32 v[128:129], v[52:53], v[152:153] op_sel_hi:[1,0]
	v_pk_mul_f32 v[154:155], v[50:51], v[152:153] op_sel_hi:[1,0]
	v_cvt_pk_bf16_f32 v128, v128, v129
	v_cvt_pk_bf16_f32 v129, v130, v131
	v_cvt_pk_bf16_f32 v130, v156, v157
	v_cvt_pk_bf16_f32 v131, v154, v155
	global_store_dwordx4 v[150:151], v[128:131], off
	v_pk_mul_f32 v[154:155], v[34:35], v[152:153] op_sel_hi:[1,0]
	v_pk_mul_f32 v[156:157], v[32:33], v[152:153] op_sel_hi:[1,0]
	v_pk_mul_f32 v[130:131], v[38:39], v[152:153] op_sel_hi:[1,0]
	v_pk_mul_f32 v[128:129], v[36:37], v[152:153] op_sel_hi:[1,0]
	s_nop 0
	v_cvt_pk_bf16_f32 v128, v128, v129
	v_cvt_pk_bf16_f32 v129, v130, v131
	v_cvt_pk_bf16_f32 v130, v156, v157
	v_cvt_pk_bf16_f32 v131, v154, v155
	global_store_dwordx4 v[150:151], v[128:131], off offset:256
	v_pk_mul_f32 v[154:155], v[2:3], v[152:153] op_sel_hi:[1,0]
	s_nop 0
	v_pk_mul_f32 v[130:131], v[6:7], v[152:153] op_sel_hi:[1,0]
	v_pk_mul_f32 v[128:129], v[4:5], v[152:153] op_sel_hi:[1,0]
	v_pk_mul_f32 v[152:153], v[0:1], v[152:153] op_sel_hi:[1,0]
	v_cvt_pk_bf16_f32 v128, v128, v129
	v_cvt_pk_bf16_f32 v129, v130, v131
	v_cvt_pk_bf16_f32 v130, v152, v153
	v_cvt_pk_bf16_f32 v131, v154, v155
	global_store_dwordx4 v[150:151], v[128:131], off offset:512
	s_cbranch_execnz .LBB0_887
.LBB0_886:
	s_nop 0
	v_and_b32_e32 v129, 64, v186
	v_xor_b32_e32 v128, 16, v186
	v_add_u32_e32 v129, 64, v129
	v_cmp_lt_i32_e32 vcc, v128, v129
	v_lshl_add_u32 v150, s70, 8, v167
	v_ashrrev_i32_e32 v151, 31, v150
	v_cndmask_b32_e32 v128, v186, v128, vcc
	v_lshlrev_b32_e32 v157, 2, v128
	v_xor_b32_e32 v128, 32, v186
	v_cmp_lt_i32_e32 vcc, v128, v129
	v_or_b32_e32 v164, 32, v150
	v_ashrrev_i32_e32 v165, 31, v164
	v_cndmask_b32_e32 v128, v186, v128, vcc
	v_lshlrev_b32_e32 v230, 2, v167
	v_add_u32_e32 v230, 0x22800, v230
	v_lshlrev_b32_e32 v155, 2, v128
	v_add_u32_e32 v172, 0x80, v150
	v_ashrrev_i32_e32 v173, 31, v172
	v_or_b32_e32 v152, 16, v150
	v_ashrrev_i32_e32 v153, 31, v152
	v_mov_b64_e32 v[158:159], s[18:19]
	s_nop 0
	ds_read_b32 v129, v230
	ds_read_b32 v128, v230 offset:64
	s_waitcnt lgkmcnt(0)
	v_pk_fma_f32 v[128:129], v[128:129], s[14:15], v[158:159] op_sel_hi:[1,0,0]
	s_nop 0
	v_mul_f32_e32 v130, 0x4b800000, v129
	v_cmp_gt_f32_e64 s[2:3], s81, v129
	v_cmp_gt_f32_e32 vcc, s81, v128
	s_nop 0
	v_cndmask_b32_e64 v129, v129, v130, s[2:3]
	v_rsq_f32_e32 v129, v129
	s_nop 0
	v_mul_f32_e32 v130, 0x45800000, v129
	v_cndmask_b32_e64 v156, v129, v130, s[2:3]
	v_mul_f32_e32 v129, 0x4b800000, v128
	v_cndmask_b32_e32 v128, v128, v129, vcc
	v_rsq_f32_e32 v128, v128
	v_pk_mul_f32 v[94:95], v[94:95], v[156:157] op_sel_hi:[1,0]
	v_pk_mul_f32 v[92:93], v[92:93], v[156:157] op_sel_hi:[1,0]
	v_pk_mul_f32 v[78:79], v[78:79], v[156:157] op_sel_hi:[1,0]
	v_mul_f32_e32 v129, 0x45800000, v128
	v_cndmask_b32_e32 v154, v128, v129, vcc
	v_pk_mul_f32 v[76:77], v[76:77], v[156:157] op_sel_hi:[1,0]
	v_pk_mul_f32 v[80:81], v[80:81], v[154:155] op_sel_hi:[1,0]
	v_pk_mul_f32 v[62:63], v[62:63], v[154:155] op_sel_hi:[1,0]
	v_pk_mul_f32 v[60:61], v[60:61], v[154:155] op_sel_hi:[1,0]
	v_or_b32_e32 v160, 48, v150
	v_ashrrev_i32_e32 v161, 31, v160
	s_nop 0
	ds_read_b32 v129, v230 offset:128
	ds_read_b32 v128, v230 offset:192
	s_waitcnt lgkmcnt(0)
	v_pk_fma_f32 v[128:129], v[128:129], s[14:15], v[158:159] op_sel_hi:[1,0,0]
	s_nop 0
	v_mul_f32_e32 v130, 0x4b800000, v129
	v_cmp_gt_f32_e64 s[2:3], s81, v129
	v_cmp_gt_f32_e32 vcc, s81, v128
	s_nop 0
	v_cndmask_b32_e64 v129, v129, v130, s[2:3]
	v_rsq_f32_e32 v129, v129
	s_nop 0
	v_mul_f32_e32 v130, 0x45800000, v129
	v_cndmask_b32_e64 v166, v129, v130, s[2:3]
	v_mul_f32_e32 v129, 0x4b800000, v128
	v_cndmask_b32_e32 v128, v128, v129, vcc
	v_rsq_f32_e32 v128, v128
	v_pk_mul_f32 v[64:65], v[64:65], v[166:167] op_sel_hi:[1,0]
	v_pk_mul_f32 v[46:47], v[46:47], v[166:167] op_sel_hi:[1,0]
	v_pk_mul_f32 v[44:45], v[44:45], v[166:167] op_sel_hi:[1,0]
	v_mul_f32_e32 v129, 0x45800000, v128
	v_cndmask_b32_e32 v162, v128, v129, vcc
	v_pk_mul_f32 v[48:49], v[48:49], v[162:163] op_sel_hi:[1,0]
	v_pk_mul_f32 v[38:39], v[38:39], v[162:163] op_sel_hi:[1,0]
	v_pk_mul_f32 v[36:37], v[36:37], v[162:163] op_sel_hi:[1,0]
	v_add_u32_e32 v168, 0x90, v150
	v_ashrrev_i32_e32 v169, 31, v168
	v_add_u32_e32 v176, 0xa0, v150
	v_ashrrev_i32_e32 v177, 31, v176
	s_nop 0
	ds_read_b32 v129, v230 offset:512
	ds_read_b32 v128, v230 offset:576
	s_waitcnt lgkmcnt(0)
	v_pk_fma_f32 v[128:129], v[128:129], s[14:15], v[158:159] op_sel_hi:[1,0,0]
	s_nop 0
	v_mul_f32_e32 v130, 0x4b800000, v129
	v_cmp_gt_f32_e64 s[2:3], s81, v129
	v_cmp_gt_f32_e32 vcc, s81, v128
	s_nop 0
	v_cndmask_b32_e64 v129, v129, v130, s[2:3]
	v_rsq_f32_e32 v129, v129
	s_nop 0
	v_mul_f32_e32 v130, 0x45800000, v129
	v_cndmask_b32_e64 v174, v129, v130, s[2:3]
	v_mul_f32_e32 v129, 0x4b800000, v128
	v_cndmask_b32_e32 v128, v128, v129, vcc
	v_rsq_f32_e32 v128, v128
	v_pk_mul_f32 v[30:31], v[30:31], v[174:175] op_sel_hi:[1,0]
	v_pk_mul_f32 v[28:29], v[28:29], v[174:175] op_sel_hi:[1,0]
	v_mul_f32_e32 v129, 0x45800000, v128
	v_cndmask_b32_e32 v170, v128, v129, vcc
	v_pk_mul_f32 v[22:23], v[22:23], v[170:171] op_sel_hi:[1,0]
	v_pk_mul_f32 v[20:21], v[20:21], v[170:171] op_sel_hi:[1,0]
	v_add_u32_e32 v178, 0xb0, v150
	v_ashrrev_i32_e32 v179, 31, v178
	v_lshl_or_b32 v180, s57, 8, v175
	v_ashrrev_i32_e32 v181, 31, v180
	s_nop 0
	ds_read_b32 v129, v230 offset:640
	ds_read_b32 v128, v230 offset:704
	s_waitcnt lgkmcnt(0)
	v_pk_fma_f32 v[128:129], v[128:129], s[14:15], v[158:159] op_sel_hi:[1,0,0]
	v_mov_b64_e32 v[158:159], s[8:9]
	v_mul_f32_e32 v130, 0x4b800000, v129
	v_cmp_gt_f32_e64 s[2:3], s81, v129
	v_cmp_gt_f32_e32 vcc, s81, v128
	s_nop 0
	v_cndmask_b32_e64 v129, v129, v130, s[2:3]
	v_rsq_f32_e32 v129, v129
	s_nop 0
	v_mul_f32_e32 v130, 0x45800000, v129
	v_cndmask_b32_e64 v130, v129, v130, s[2:3]
	v_mad_i64_i32 v[188:189], s[2:3], v150, s94, v[158:159]
	v_lshlrev_b64 v[150:151], 1, v[180:181]
	v_lshl_add_u64 v[180:181], v[188:189], 0, v[150:151]
	v_pk_mul_f32 v[188:189], v[90:91], v[156:157] op_sel_hi:[1,0]
	v_pk_mul_f32 v[90:91], v[88:89], v[156:157] op_sel_hi:[1,0]
	v_cvt_pk_bf16_f32 v88, v92, v93
	v_cvt_pk_bf16_f32 v89, v94, v95
	v_cvt_pk_bf16_f32 v90, v90, v91
	v_cvt_pk_bf16_f32 v91, v188, v189
	global_store_dwordx4 v[180:181], v[88:91], off
	v_mul_f32_e32 v129, 0x4b800000, v128
	v_cndmask_b32_e32 v128, v128, v129, vcc
	v_pk_mul_f32 v[88:89], v[74:75], v[156:157] op_sel_hi:[1,0]
	v_pk_mul_f32 v[74:75], v[72:73], v[156:157] op_sel_hi:[1,0]
	v_cvt_pk_bf16_f32 v72, v76, v77
	v_cvt_pk_bf16_f32 v73, v78, v79
	v_cvt_pk_bf16_f32 v74, v74, v75
	v_cvt_pk_bf16_f32 v75, v88, v89
	global_store_dwordx4 v[180:181], v[72:75], off offset:256
	v_pk_mul_f32 v[78:79], v[82:83], v[154:155] op_sel_hi:[1,0]
	v_rsq_f32_e32 v128, v128
	v_mad_i64_i32 v[72:73], s[2:3], v152, s94, v[158:159]
	v_lshl_add_u64 v[76:77], v[72:73], 0, v[150:151]
	v_pk_mul_f32 v[74:75], v[86:87], v[154:155] op_sel_hi:[1,0]
	v_pk_mul_f32 v[72:73], v[84:85], v[154:155] op_sel_hi:[1,0]
	v_pk_mul_f32 v[14:15], v[14:15], v[130:131] op_sel_hi:[1,0]
	v_cvt_pk_bf16_f32 v72, v72, v73
	v_cvt_pk_bf16_f32 v73, v74, v75
	v_cvt_pk_bf16_f32 v74, v80, v81
	v_cvt_pk_bf16_f32 v75, v78, v79
	global_store_dwordx4 v[76:77], v[72:75], off
	v_pk_mul_f32 v[12:13], v[12:13], v[130:131] op_sel_hi:[1,0]
	v_mul_f32_e32 v129, 0x45800000, v128
	v_pk_mul_f32 v[72:73], v[58:59], v[154:155] op_sel_hi:[1,0]
	v_pk_mul_f32 v[58:59], v[56:57], v[154:155] op_sel_hi:[1,0]
	v_cvt_pk_bf16_f32 v56, v60, v61
	v_cvt_pk_bf16_f32 v57, v62, v63
	v_cvt_pk_bf16_f32 v58, v58, v59
	v_cvt_pk_bf16_f32 v59, v72, v73
	global_store_dwordx4 v[76:77], v[56:59], off offset:256
	v_pk_mul_f32 v[62:63], v[66:67], v[166:167] op_sel_hi:[1,0]
	v_cndmask_b32_e32 v128, v128, v129, vcc
	v_mad_i64_i32 v[56:57], s[2:3], v164, s94, v[158:159]
	v_lshl_add_u64 v[60:61], v[56:57], 0, v[150:151]
	v_pk_mul_f32 v[58:59], v[70:71], v[166:167] op_sel_hi:[1,0]
	v_pk_mul_f32 v[56:57], v[68:69], v[166:167] op_sel_hi:[1,0]
	v_pk_mul_f32 v[6:7], v[6:7], v[128:129] op_sel_hi:[1,0]
	v_cvt_pk_bf16_f32 v56, v56, v57
	v_cvt_pk_bf16_f32 v57, v58, v59
	v_cvt_pk_bf16_f32 v58, v64, v65
	v_cvt_pk_bf16_f32 v59, v62, v63
	global_store_dwordx4 v[60:61], v[56:59], off
	v_pk_mul_f32 v[4:5], v[4:5], v[128:129] op_sel_hi:[1,0]
	s_nop 0
	v_pk_mul_f32 v[56:57], v[42:43], v[166:167] op_sel_hi:[1,0]
	v_pk_mul_f32 v[42:43], v[40:41], v[166:167] op_sel_hi:[1,0]
	v_cvt_pk_bf16_f32 v40, v44, v45
	v_cvt_pk_bf16_f32 v41, v46, v47
	v_cvt_pk_bf16_f32 v42, v42, v43
	v_cvt_pk_bf16_f32 v43, v56, v57
	global_store_dwordx4 v[60:61], v[40:43], off offset:256
	v_pk_mul_f32 v[46:47], v[50:51], v[162:163] op_sel_hi:[1,0]
	s_nop 0
	v_mad_i64_i32 v[40:41], s[2:3], v160, s94, v[158:159]
	v_lshl_add_u64 v[44:45], v[40:41], 0, v[150:151]
	v_pk_mul_f32 v[42:43], v[54:55], v[162:163] op_sel_hi:[1,0]
	v_pk_mul_f32 v[40:41], v[52:53], v[162:163] op_sel_hi:[1,0]
	s_nop 0
	v_cvt_pk_bf16_f32 v40, v40, v41
	v_cvt_pk_bf16_f32 v41, v42, v43
	v_cvt_pk_bf16_f32 v42, v48, v49
	v_cvt_pk_bf16_f32 v43, v46, v47
	global_store_dwordx4 v[44:45], v[40:43], off
	s_nop 1
	v_pk_mul_f32 v[40:41], v[34:35], v[162:163] op_sel_hi:[1,0]
	v_pk_mul_f32 v[34:35], v[32:33], v[162:163] op_sel_hi:[1,0]
	v_cvt_pk_bf16_f32 v32, v36, v37
	v_cvt_pk_bf16_f32 v33, v38, v39
	v_cvt_pk_bf16_f32 v34, v34, v35
	v_cvt_pk_bf16_f32 v35, v40, v41
	global_store_dwordx4 v[44:45], v[32:35], off offset:256
	s_nop 1
	v_mad_i64_i32 v[32:33], s[2:3], v172, s94, v[158:159]
	v_pk_mul_f32 v[34:35], v[26:27], v[174:175] op_sel_hi:[1,0]
	v_pk_mul_f32 v[26:27], v[24:25], v[174:175] op_sel_hi:[1,0]
	v_lshl_add_u64 v[32:33], v[32:33], 0, v[150:151]
	v_cvt_pk_bf16_f32 v24, v28, v29
	v_cvt_pk_bf16_f32 v25, v30, v31
	v_cvt_pk_bf16_f32 v26, v26, v27
	v_cvt_pk_bf16_f32 v27, v34, v35
	global_store_dwordx4 v[32:33], v[24:27], off
	v_pk_mul_f32 v[28:29], v[122:123], v[174:175] op_sel_hi:[1,0]
	v_pk_mul_f32 v[30:31], v[120:121], v[174:175] op_sel_hi:[1,0]
	v_pk_mul_f32 v[26:27], v[126:127], v[174:175] op_sel_hi:[1,0]
	v_pk_mul_f32 v[24:25], v[124:125], v[174:175] op_sel_hi:[1,0]
	s_nop 0
	v_cvt_pk_bf16_f32 v24, v24, v25
	v_cvt_pk_bf16_f32 v25, v26, v27
	v_cvt_pk_bf16_f32 v26, v30, v31
	v_cvt_pk_bf16_f32 v27, v28, v29
	global_store_dwordx4 v[32:33], v[24:27], off offset:256
	s_nop 1
	v_mad_i64_i32 v[24:25], s[2:3], v168, s94, v[158:159]
	v_pk_mul_f32 v[26:27], v[18:19], v[170:171] op_sel_hi:[1,0]
	v_pk_mul_f32 v[18:19], v[16:17], v[170:171] op_sel_hi:[1,0]
	v_lshl_add_u64 v[24:25], v[24:25], 0, v[150:151]
	v_cvt_pk_bf16_f32 v16, v20, v21
	v_cvt_pk_bf16_f32 v17, v22, v23
	v_cvt_pk_bf16_f32 v18, v18, v19
	v_cvt_pk_bf16_f32 v19, v26, v27
	global_store_dwordx4 v[24:25], v[16:19], off
	v_pk_mul_f32 v[20:21], v[114:115], v[170:171] op_sel_hi:[1,0]
	v_pk_mul_f32 v[22:23], v[112:113], v[170:171] op_sel_hi:[1,0]
	v_pk_mul_f32 v[18:19], v[118:119], v[170:171] op_sel_hi:[1,0]
	v_pk_mul_f32 v[16:17], v[116:117], v[170:171] op_sel_hi:[1,0]
	s_nop 0
	v_cvt_pk_bf16_f32 v16, v16, v17
	v_cvt_pk_bf16_f32 v17, v18, v19
	v_cvt_pk_bf16_f32 v18, v22, v23
	v_cvt_pk_bf16_f32 v19, v20, v21
	global_store_dwordx4 v[24:25], v[16:19], off offset:256
	s_nop 1
	v_mad_i64_i32 v[16:17], s[2:3], v176, s94, v[158:159]
	v_pk_mul_f32 v[18:19], v[10:11], v[130:131] op_sel_hi:[1,0]
	v_pk_mul_f32 v[10:11], v[8:9], v[130:131] op_sel_hi:[1,0]
	v_lshl_add_u64 v[16:17], v[16:17], 0, v[150:151]
	v_cvt_pk_bf16_f32 v8, v12, v13
	v_cvt_pk_bf16_f32 v9, v14, v15
	v_cvt_pk_bf16_f32 v10, v10, v11
	v_cvt_pk_bf16_f32 v11, v18, v19
	global_store_dwordx4 v[16:17], v[8:11], off
	v_pk_mul_f32 v[12:13], v[106:107], v[130:131] op_sel_hi:[1,0]
	v_pk_mul_f32 v[14:15], v[104:105], v[130:131] op_sel_hi:[1,0]
	v_pk_mul_f32 v[10:11], v[110:111], v[130:131] op_sel_hi:[1,0]
	v_pk_mul_f32 v[8:9], v[108:109], v[130:131] op_sel_hi:[1,0]
	s_nop 0
	v_cvt_pk_bf16_f32 v8, v8, v9
	v_cvt_pk_bf16_f32 v9, v10, v11
	v_cvt_pk_bf16_f32 v10, v14, v15
	v_cvt_pk_bf16_f32 v11, v12, v13
	global_store_dwordx4 v[16:17], v[8:11], off offset:256
	s_nop 1
	v_mad_i64_i32 v[8:9], s[2:3], v178, s94, v[158:159]
	v_pk_mul_f32 v[10:11], v[2:3], v[128:129] op_sel_hi:[1,0]
	v_pk_mul_f32 v[2:3], v[0:1], v[128:129] op_sel_hi:[1,0]
	v_lshl_add_u64 v[8:9], v[8:9], 0, v[150:151]
	v_cvt_pk_bf16_f32 v0, v4, v5
	v_cvt_pk_bf16_f32 v1, v6, v7
	v_cvt_pk_bf16_f32 v2, v2, v3
	v_cvt_pk_bf16_f32 v3, v10, v11
	global_store_dwordx4 v[8:9], v[0:3], off
	v_pk_mul_f32 v[4:5], v[98:99], v[128:129] op_sel_hi:[1,0]
	v_pk_mul_f32 v[6:7], v[96:97], v[128:129] op_sel_hi:[1,0]
	v_pk_mul_f32 v[2:3], v[102:103], v[128:129] op_sel_hi:[1,0]
	v_pk_mul_f32 v[0:1], v[100:101], v[128:129] op_sel_hi:[1,0]
	s_nop 0
	v_cvt_pk_bf16_f32 v0, v0, v1
	v_cvt_pk_bf16_f32 v1, v2, v3
	v_cvt_pk_bf16_f32 v2, v6, v7
	v_cvt_pk_bf16_f32 v3, v4, v5
	global_store_dwordx4 v[8:9], v[0:3], off offset:256
